# ln1 row loop: gamma/beta and scale/shift loads of chunks 1-3 issued together before the wave sums (one round trip instead of seven)
# speedup vs baseline: 1.0061x; 1.0047x over previous
.LBB0_589:
	v_add_u32_e32 v0, 0xfffff000, v18
	v_lshrrev_b32_e32 v0, 12, v0
	v_lshl_add_u64 v[74:75], s[8:9], 0, v[32:33]
	v_add_u32_e32 v19, 1, v0
	v_add_co_u32_e32 v0, vcc, 0x1874b000, v74
	v_mov_b64_e32 v[44:45], s[12:13]
	s_nop 0
	v_addc_co_u32_e32 v1, vcc, 0, v75, vcc
	v_cmp_lt_i32_e32 vcc, s18, v18
	v_lshl_add_u64 v[110:111], s[8:9], 0, v[34:35]
	v_mov_b32_e32 v37, v16
	v_cndmask_b32_e32 v19, 0, v19, vcc
	v_add_u32_e32 v19, s60, v19
	v_mad_u64_u32 v[44:45], s[16:17], v19, s41, v[44:45]
	s_mov_b64 s[16:17], 0x4000
	s_nop 0
	v_lshl_add_u64 v[72:73], v[44:45], 0, s[16:17]
	s_mov_b64 s[16:17], 0x8000
	v_lshl_add_u64 v[52:53], v[44:45], 0, s[16:17]
	s_mov_b64 s[16:17], 0x6000
	v_lshl_add_u64 v[54:55], v[44:45], 0, s[16:17]
	s_mov_b32 s16, 0x1274b000
	v_add_co_u32_e32 v46, vcc, s16, v110
	v_lshl_add_u64 v[44:45], v[110:111], 0, s[20:21]
	s_nop 0
	v_addc_co_u32_e32 v47, vcc, 0, v111, vcc
	global_load_dwordx4 v[12:15], v[0:1], off offset:512
	global_load_dwordx4 v[8:11], v[0:1], off offset:1536
	global_load_dwordx4 v[4:7], v[0:1], off offset:2560
	s_nop 0
	global_load_dwordx4 v[0:3], v[0:1], off offset:3584
	s_nop 0
	global_load_dwordx4 v[48:51], v[46:47], off offset:512
	global_load_dwordx4 v[56:59], v[44:45], off offset:16
	v_lshl_add_u64 v[44:45], v[72:73], 0, v[36:37]
	global_load_dwordx4 v[60:63], v[44:45], off
	global_load_dwordx4 v[64:67], v[44:45], off offset:16
	s_mov_b64 s[16:17], 0x1274ba00
	v_lshl_add_u64 v[44:45], v[110:111], 0, s[16:17]
	v_mov_b32_e32 v39, v16
	s_mov_b64 s[16:17], 0x1274c200
	global_load_dwordx4 v[68:71], v[46:47], off offset:2560
	global_load_dwordx4 v[82:85], v[44:45], off offset:16
	v_lshl_add_u64 v[44:45], v[72:73], 0, v[38:39]
	v_lshl_add_u64 v[98:99], v[110:111], 0, s[16:17]
	s_mov_b32 s16, 0x1274c000
	global_load_dwordx4 v[86:89], v[44:45], off
	global_load_dwordx4 v[90:93], v[44:45], off offset:16
	v_add_co_u32_e32 v44, vcc, s16, v110
	v_mov_b32_e32 v41, v16
	s_mov_b64 s[16:17], 0x1274ca00
	v_mov_b32_e32 v43, v16
	v_addc_co_u32_e32 v45, vcc, 0, v111, vcc
	v_lshl_add_u64 v[106:107], v[72:73], 0, v[40:41]
	v_lshl_add_u64 v[114:115], v[110:111], 0, s[16:17]
	v_lshl_add_u64 v[72:73], v[72:73], 0, v[42:43]
	global_load_dwordx4 v[94:97], v[44:45], off offset:512
	s_nop 0
	global_load_dwordx4 v[98:101], v[98:99], off offset:16
	s_nop 0
	global_load_dwordx4 v[102:105], v[106:107], off
	s_nop 0
	global_load_dwordx4 v[106:109], v[106:107], off offset:16
	s_nop 0
	global_load_dwordx4 v[110:113], v[44:45], off offset:2560
	s_nop 0
	global_load_dwordx4 v[114:117], v[114:115], off offset:16
	s_nop 0
	global_load_dwordx4 v[118:121], v[72:73], off
	global_load_dwordx4 v[122:125], v[72:73], off offset:16
	v_lshl_add_u64 v[138:139], v[54:55], 0, v[36:37]
	s_mov_b32 s16, 0x1b74b000
	v_add_u32_e32 v18, s72, v18
	v_lshl_add_u64 v[32:33], v[32:33], 0, s[0:1]
	v_lshl_add_u64 v[34:35], v[34:35], 0, s[70:71]
	s_waitcnt vmcnt(0)
	v_lshlrev_b32_e32 v134, 16, v14
	v_and_b32_e32 v135, 0xffff0000, v14
	v_lshlrev_b32_e32 v14, 16, v15
	v_and_b32_e32 v15, 0xffff0000, v15
	v_and_b32_e32 v73, 0xffff0000, v2
	v_lshlrev_b32_e32 v72, 16, v2
	v_pk_mul_f32 v[14:15], v[66:67], v[14:15]
	v_pk_mul_f32 v[64:65], v[64:65], v[134:135]
	v_pk_fma_f32 v[58:59], v[58:59], s[86:87], v[14:15] op_sel_hi:[1,0,1]
	v_lshlrev_b32_e32 v14, 16, v12
	v_and_b32_e32 v15, 0xffff0000, v12
	v_pk_mul_f32 v[14:15], v[60:61], v[14:15]
	v_pk_fma_f32 v[56:57], v[56:57], s[86:87], v[64:65] op_sel_hi:[1,0,1]
	v_pk_fma_f32 v[66:67], v[48:49], s[86:87], v[14:15] op_sel_hi:[1,0,1]
	v_lshl_add_u64 v[64:65], v[52:53], 0, v[38:39]
	v_add_f32_e32 v12, 0, v66
	v_add_f32_e32 v14, v67, v12
	v_lshlrev_b32_e32 v12, 16, v13
	v_and_b32_e32 v13, 0xffff0000, v13
	v_pk_mul_f32 v[12:13], v[62:63], v[12:13]
	v_lshl_add_u64 v[60:61], v[54:55], 0, v[38:39]
	v_pk_fma_f32 v[62:63], v[50:51], s[86:87], v[12:13] op_sel_hi:[1,0,1]
	v_pk_mul_f32 v[72:73], v[122:123], v[72:73]
	v_add_f32_e32 v12, v62, v14
	v_add_f32_e32 v12, v63, v12
	v_add_f32_e32 v12, v56, v12
	v_pk_fma_f32 v[142:143], v[114:115], s[86:87], v[72:73] op_sel_hi:[1,0,1]
	v_and_b32_e32 v73, 0xffff0000, v3
	v_lshlrev_b32_e32 v72, 16, v3
	v_add_f32_e32 v12, v57, v12
	v_pk_mul_f32 v[2:3], v[124:125], v[72:73]
	v_lshl_add_u64 v[72:73], v[52:53], 0, v[36:37]
	v_add_f32_e32 v12, v58, v12
	v_pk_fma_f32 v[2:3], v[116:117], s[86:87], v[2:3] op_sel_hi:[1,0,1]
	global_load_dwordx4 v[114:117], v[20:21], off
	global_load_dwordx4 v[122:125], v[20:21], off offset:16
	global_load_dwordx4 v[126:129], v[22:23], off
	global_load_dwordx4 v[130:133], v[22:23], off offset:16
	v_add_f32_e32 v19, v59, v12
	global_load_dwordx4 v[12:15], v[72:73], off offset:16
	global_load_dwordx4 v[48:51], v[72:73], off
	global_load_dwordx4 v[134:137], v[138:139], off offset:16
	s_nop 0
	global_load_dwordx4 v[138:141], v[138:139], off
	s_waitcnt vmcnt(3)
	v_pk_add_f32 v[150:151], v[14:15], 1.0 op_sel_hi:[1,0]
	v_lshlrev_b32_e32 v14, 16, v8
	v_and_b32_e32 v15, 0xffff0000, v8
	v_pk_mul_f32 v[14:15], v[86:87], v[14:15]
	v_pk_add_f32 v[148:149], v[12:13], 1.0 op_sel_hi:[1,0]
	v_pk_fma_f32 v[14:15], v[68:69], s[86:87], v[14:15] op_sel_hi:[1,0,1]
	v_lshlrev_b32_e32 v12, 16, v10
	v_add_f32_e32 v8, v14, v19
	v_add_f32_e32 v19, v15, v8
	v_lshlrev_b32_e32 v8, 16, v9
	v_and_b32_e32 v9, 0xffff0000, v9
	v_pk_mul_f32 v[8:9], v[88:89], v[8:9]
	v_and_b32_e32 v13, 0xffff0000, v10
	v_pk_fma_f32 v[8:9], v[70:71], s[86:87], v[8:9] op_sel_hi:[1,0,1]
	v_pk_mul_f32 v[12:13], v[90:91], v[12:13]
	v_add_f32_e32 v19, v8, v19
	v_pk_fma_f32 v[12:13], v[82:83], s[86:87], v[12:13] op_sel_hi:[1,0,1]
	v_lshlrev_b32_e32 v10, 16, v11
	v_and_b32_e32 v11, 0xffff0000, v11
	v_add_f32_e32 v19, v9, v19
	v_lshlrev_b32_e32 v68, 16, v6
	v_and_b32_e32 v69, 0xffff0000, v6
	v_lshlrev_b32_e32 v6, 16, v7
	v_and_b32_e32 v7, 0xffff0000, v7
	v_pk_mul_f32 v[10:11], v[92:93], v[10:11]
	v_add_f32_e32 v19, v12, v19
	v_pk_mul_f32 v[6:7], v[108:109], v[6:7]
	v_pk_fma_f32 v[10:11], v[84:85], s[86:87], v[10:11] op_sel_hi:[1,0,1]
	v_add_f32_e32 v19, v13, v19
	v_pk_fma_f32 v[84:85], v[100:101], s[86:87], v[6:7] op_sel_hi:[1,0,1]
	v_lshlrev_b32_e32 v6, 16, v4
	v_and_b32_e32 v7, 0xffff0000, v4
	v_add_f32_e32 v19, v10, v19
	v_pk_mul_f32 v[6:7], v[102:103], v[6:7]
	v_add_f32_e32 v19, v11, v19
	v_pk_fma_f32 v[86:87], v[94:95], s[86:87], v[6:7] op_sel_hi:[1,0,1]
	v_pk_mul_f32 v[68:69], v[106:107], v[68:69]
	v_add_f32_e32 v4, v86, v19
	v_add_f32_e32 v6, v87, v4
	v_lshlrev_b32_e32 v4, 16, v5
	v_and_b32_e32 v5, 0xffff0000, v5
	v_pk_mul_f32 v[4:5], v[104:105], v[4:5]
	v_pk_fma_f32 v[82:83], v[98:99], s[86:87], v[68:69] op_sel_hi:[1,0,1]
	v_pk_fma_f32 v[88:89], v[96:97], s[86:87], v[4:5] op_sel_hi:[1,0,1]
	s_waitcnt vmcnt(2)
	v_pk_add_f32 v[146:147], v[50:51], 1.0 op_sel_hi:[1,0]
	v_add_f32_e32 v4, v88, v6
	v_add_f32_e32 v4, v89, v4
	v_add_f32_e32 v4, v82, v4
	v_lshl_add_u64 v[50:51], v[52:53], 0, v[40:41]
	v_add_f32_e32 v4, v83, v4
	v_lshl_add_u64 v[6:7], v[52:53], 0, v[42:43]
	v_lshlrev_b32_e32 v52, 16, v0
	v_and_b32_e32 v53, 0xffff0000, v0
	v_add_f32_e32 v4, v84, v4
	v_pk_mul_f32 v[52:53], v[118:119], v[52:53]
	v_add_f32_e32 v19, v85, v4
	v_pk_fma_f32 v[52:53], v[110:111], s[86:87], v[52:53] op_sel_hi:[1,0,1]
	v_pk_add_f32 v[144:145], v[48:49], 1.0 op_sel_hi:[1,0]
	v_add_f32_e32 v0, v52, v19
	v_add_f32_e32 v19, v53, v0
	v_lshlrev_b32_e32 v0, 16, v1
	v_and_b32_e32 v1, 0xffff0000, v1
	v_pk_mul_f32 v[0:1], v[120:121], v[0:1]
	v_lshl_add_u64 v[48:49], v[54:55], 0, v[40:41]
	v_pk_fma_f32 v[0:1], v[112:113], s[86:87], v[0:1] op_sel_hi:[1,0,1]
	v_lshl_add_u64 v[4:5], v[54:55], 0, v[42:43]
	global_load_dwordx4 v[152:155], v[20:21], off offset:2048
	global_load_dwordx4 v[156:159], v[20:21], off offset:2064
	global_load_dwordx4 v[160:163], v[22:23], off offset:2048
	global_load_dwordx4 v[164:167], v[22:23], off offset:2064
	global_load_dwordx4 v[168:171], v[24:25], off
	global_load_dwordx4 v[172:175], v[24:25], off offset:16
	global_load_dwordx4 v[176:179], v[26:27], off
	global_load_dwordx4 v[180:183], v[26:27], off offset:16
	global_load_dwordx4 v[214:217], v[28:29], off
	global_load_dwordx4 v[218:221], v[28:29], off offset:16
	global_load_dwordx4 v[222:225], v[30:31], off
	global_load_dwordx4 v[226:229], v[30:31], off offset:16
	global_load_dwordx4 v[230:233], v[64:65], off
	global_load_dwordx4 v[234:237], v[64:65], off offset:16
	global_load_dwordx4 v[238:241], v[60:61], off
	global_load_dwordx4 v[242:245], v[60:61], off offset:16
	global_load_dwordx4 v[196:199], v[50:51], off
	global_load_dwordx4 v[200:203], v[50:51], off offset:16
	global_load_dwordx4 v[204:207], v[48:49], off
	global_load_dwordx4 v[208:211], v[48:49], off offset:16
	v_add_f32_e32 v19, v0, v19
	v_add_f32_e32 v19, v1, v19
	v_add_f32_e32 v19, v142, v19
	v_add_f32_e32 v19, v143, v19
	v_add_f32_e32 v19, v2, v19
	v_add_f32_e32 v19, v3, v19
	s_waitcnt lgkmcnt(0)
	v_mov_b32_e32 v37, v19
	s_nop 1
	v_permlane32_swap_b32_e32 v37, v19
	v_add_f32_e32 v19, v19, v37
	v_mov_b32_e32 v37, v19
	s_nop 1
	v_permlane16_swap_b32_e32 v37, v19
	v_add_f32_e32 v19, v19, v37
	s_nop 1
	v_add_f32_dpp v19, v19, v19 row_ror:8 row_mask:0xf bank_mask:0xf
	s_nop 1
	v_add_f32_dpp v19, v19, v19 row_ror:4 row_mask:0xf bank_mask:0xf
	s_nop 1
	v_add_f32_dpp v19, v19, v19 row_ror:2 row_mask:0xf bank_mask:0xf
	s_nop 1
	v_add_f32_dpp v19, v19, v19 row_ror:1 row_mask:0xf bank_mask:0xf
	v_mul_f32_e32 v90, 0x3a000000, v19
	v_pk_add_f32 v[92:93], v[66:67], v[90:91] op_sel_hi:[1,0] neg_lo:[0,1] neg_hi:[0,1]
	v_pk_add_f32 v[96:97], v[62:63], v[90:91] op_sel_hi:[1,0] neg_lo:[0,1] neg_hi:[0,1]
	v_pk_mul_f32 v[94:95], v[92:93], v[92:93]
	v_pk_mul_f32 v[98:99], v[96:97], v[96:97]
	v_add_f32_e32 v19, v94, v95
	v_pk_add_f32 v[100:101], v[56:57], v[90:91] op_sel_hi:[1,0] neg_lo:[0,1] neg_hi:[0,1]
	v_add_f32_e32 v19, v98, v19
	v_pk_mul_f32 v[102:103], v[100:101], v[100:101]
	v_add_f32_e32 v19, v99, v19
	v_pk_add_f32 v[104:105], v[58:59], v[90:91] op_sel_hi:[1,0] neg_lo:[0,1] neg_hi:[0,1]
	v_add_f32_e32 v19, v102, v19
	v_pk_mul_f32 v[106:107], v[104:105], v[104:105]
	v_add_f32_e32 v19, v103, v19
	v_pk_add_f32 v[72:73], v[14:15], v[90:91] op_sel_hi:[1,0] neg_lo:[0,1] neg_hi:[0,1]
	v_add_f32_e32 v19, v106, v19
	v_pk_mul_f32 v[108:109], v[72:73], v[72:73]
	v_add_f32_e32 v19, v107, v19
	v_pk_add_f32 v[68:69], v[8:9], v[90:91] op_sel_hi:[1,0] neg_lo:[0,1] neg_hi:[0,1]
	v_add_f32_e32 v19, v108, v19
	v_pk_mul_f32 v[110:111], v[68:69], v[68:69]
	v_add_f32_e32 v19, v109, v19
	v_pk_add_f32 v[70:71], v[12:13], v[90:91] op_sel_hi:[1,0] neg_lo:[0,1] neg_hi:[0,1]
	v_add_f32_e32 v19, v110, v19
	v_pk_mul_f32 v[112:113], v[70:71], v[70:71]
	v_add_f32_e32 v19, v111, v19
	v_pk_add_f32 v[66:67], v[10:11], v[90:91] op_sel_hi:[1,0] neg_lo:[0,1] neg_hi:[0,1]
	v_add_f32_e32 v19, v112, v19
	v_pk_mul_f32 v[118:119], v[66:67], v[66:67]
	v_add_f32_e32 v19, v113, v19
	v_pk_add_f32 v[62:63], v[86:87], v[90:91] op_sel_hi:[1,0] neg_lo:[0,1] neg_hi:[0,1]
	v_add_f32_e32 v19, v118, v19
	v_pk_mul_f32 v[86:87], v[62:63], v[62:63]
	v_add_f32_e32 v19, v119, v19
	v_pk_add_f32 v[56:57], v[88:89], v[90:91] op_sel_hi:[1,0] neg_lo:[0,1] neg_hi:[0,1]
	v_add_f32_e32 v19, v86, v19
	v_pk_mul_f32 v[88:89], v[56:57], v[56:57]
	v_add_f32_e32 v19, v87, v19
	v_pk_add_f32 v[58:59], v[82:83], v[90:91] op_sel_hi:[1,0] neg_lo:[0,1] neg_hi:[0,1]
	v_add_f32_e32 v19, v88, v19
	v_pk_mul_f32 v[82:83], v[58:59], v[58:59]
	v_add_f32_e32 v19, v89, v19
	v_pk_add_f32 v[54:55], v[84:85], v[90:91] op_sel_hi:[1,0] neg_lo:[0,1] neg_hi:[0,1]
	v_add_f32_e32 v19, v82, v19
	v_pk_mul_f32 v[84:85], v[54:55], v[54:55]
	v_add_f32_e32 v19, v83, v19
	v_pk_add_f32 v[14:15], v[52:53], v[90:91] op_sel_hi:[1,0] neg_lo:[0,1] neg_hi:[0,1]
	v_add_f32_e32 v19, v84, v19
	v_pk_mul_f32 v[52:53], v[14:15], v[14:15]
	v_add_f32_e32 v19, v85, v19
	v_pk_add_f32 v[10:11], v[0:1], v[90:91] op_sel_hi:[1,0] neg_lo:[0,1] neg_hi:[0,1]
	v_add_f32_e32 v19, v52, v19
	v_pk_mul_f32 v[0:1], v[10:11], v[10:11]
	v_add_f32_e32 v19, v53, v19
	v_pk_add_f32 v[12:13], v[142:143], v[90:91] op_sel_hi:[1,0] neg_lo:[0,1] neg_hi:[0,1]
	v_add_f32_e32 v0, v0, v19
	v_pk_mul_f32 v[120:121], v[12:13], v[12:13]
	v_add_f32_e32 v0, v1, v0
	v_pk_add_f32 v[8:9], v[2:3], v[90:91] op_sel_hi:[1,0] neg_lo:[0,1] neg_hi:[0,1]
	v_add_f32_e32 v0, v120, v0
	v_pk_mul_f32 v[2:3], v[8:9], v[8:9]
	v_add_f32_e32 v0, v121, v0
	v_add_f32_e32 v0, v2, v0
	v_add_f32_e32 v0, v3, v0
	s_waitcnt lgkmcnt(0)
	v_mov_b32_e32 v1, v0
	s_nop 1
	v_permlane32_swap_b32_e32 v1, v0
	v_add_f32_e32 v0, v0, v1
	v_mov_b32_e32 v1, v0
	s_nop 1
	v_permlane16_swap_b32_e32 v1, v0
	v_add_f32_e32 v0, v0, v1
	s_nop 1
	v_add_f32_dpp v0, v0, v0 row_ror:8 row_mask:0xf bank_mask:0xf
	s_nop 1
	v_add_f32_dpp v0, v0, v0 row_ror:4 row_mask:0xf bank_mask:0xf
	s_nop 1
	v_add_f32_dpp v0, v0, v0 row_ror:2 row_mask:0xf bank_mask:0xf
	s_nop 1
	v_add_f32_dpp v0, v0, v0 row_ror:1 row_mask:0xf bank_mask:0xf
	v_fmamk_f32 v0, v0, 0x3a000000, v186
	v_cmp_gt_f32_e32 vcc, s54, v0
	v_mul_f32_e32 v1, 0x4b800000, v0
	s_nop 0
	v_cndmask_b32_e32 v0, v0, v1, vcc
	v_rsq_f32_e32 v0, v0
	s_nop 0
	v_mul_f32_e32 v1, 0x45800000, v0
	v_cndmask_b32_e32 v52, v0, v1, vcc
	v_pk_mul_f32 v[2:3], v[100:101], v[52:53] op_sel_hi:[1,0]
	v_pk_mul_f32 v[0:1], v[92:93], v[52:53] op_sel_hi:[1,0]
	v_pk_fma_f32 v[82:83], v[122:123], v[2:3], v[130:131]
	v_pk_mul_f32 v[2:3], v[96:97], v[52:53] op_sel_hi:[1,0]
	v_pk_fma_f32 v[0:1], v[114:115], v[0:1], v[126:127]
	v_pk_fma_f32 v[2:3], v[116:117], v[2:3], v[128:129]
	v_pk_mul_f32 v[84:85], v[104:105], v[52:53] op_sel_hi:[1,0]
	v_add_co_u32_e32 v74, vcc, s16, v74
	v_pk_fma_f32 v[84:85], v[124:125], v[84:85], v[132:133]
	global_store_dwordx4 v[46:47], v[0:3], off offset:512
	global_store_dwordx4 v[46:47], v[82:85], off offset:528
	v_addc_co_u32_e32 v75, vcc, 0, v75, vcc
	s_waitcnt vmcnt(2)
	v_pk_fma_f32 v[0:1], v[144:145], v[0:1], v[138:139]
	v_pk_fma_f32 v[2:3], v[146:147], v[2:3], v[140:141]
	v_cvt_pk_bf16_f32 v0, v0, v1
	v_cvt_pk_bf16_f32 v1, v2, v3
	v_pk_fma_f32 v[2:3], v[148:149], v[82:83], v[134:135]
	v_pk_fma_f32 v[82:83], v[150:151], v[84:85], v[136:137]
	v_cvt_pk_bf16_f32 v2, v2, v3
	v_cvt_pk_bf16_f32 v3, v82, v83
	global_store_dwordx4 v[74:75], v[0:3], off offset:512
	global_load_dwordx4 v[114:117], v[6:7], off
	global_load_dwordx4 v[118:121], v[6:7], off offset:16
	global_load_dwordx4 v[122:125], v[4:5], off
	global_load_dwordx4 v[126:129], v[4:5], off offset:16
	v_pk_mul_f32 v[72:73], v[72:73], v[52:53] op_sel_hi:[1,0]
	v_pk_mul_f32 v[68:69], v[68:69], v[52:53] op_sel_hi:[1,0]
	v_pk_mul_f32 v[70:71], v[70:71], v[52:53] op_sel_hi:[1,0]
	v_pk_mul_f32 v[66:67], v[66:67], v[52:53] op_sel_hi:[1,0]
	v_pk_mul_f32 v[14:15], v[14:15], v[52:53] op_sel_hi:[1,0]
	v_pk_mul_f32 v[10:11], v[10:11], v[52:53] op_sel_hi:[1,0]
	v_pk_mul_f32 v[12:13], v[12:13], v[52:53] op_sel_hi:[1,0]
	v_pk_mul_f32 v[8:9], v[8:9], v[52:53] op_sel_hi:[1,0]
	v_pk_mul_f32 v[62:63], v[62:63], v[52:53] op_sel_hi:[1,0]
	v_pk_mul_f32 v[56:57], v[56:57], v[52:53] op_sel_hi:[1,0]
	v_pk_mul_f32 v[58:59], v[58:59], v[52:53] op_sel_hi:[1,0]
	v_pk_mul_f32 v[54:55], v[54:55], v[52:53] op_sel_hi:[1,0]
	s_movk_i32 s16, 0x2fff
	v_cmp_lt_i32_e32 vcc, s16, v18
	s_or_b64 s[14:15], vcc, s[14:15]
	v_pk_fma_f32 v[152:153], v[152:153], v[72:73], v[160:161]
	v_pk_fma_f32 v[154:155], v[154:155], v[68:69], v[162:163]
	v_pk_fma_f32 v[156:157], v[156:157], v[70:71], v[164:165]
	v_pk_fma_f32 v[158:159], v[158:159], v[66:67], v[166:167]
	global_store_dwordx4 v[46:47], v[152:155], off offset:2560
	global_store_dwordx4 v[46:47], v[156:159], off offset:2576
	v_pk_add_f32 v[230:231], v[230:231], 1.0 op_sel_hi:[1,0]
	v_pk_add_f32 v[232:233], v[232:233], 1.0 op_sel_hi:[1,0]
	v_pk_add_f32 v[234:235], v[234:235], 1.0 op_sel_hi:[1,0]
	v_pk_add_f32 v[236:237], v[236:237], 1.0 op_sel_hi:[1,0]
	v_pk_fma_f32 v[230:231], v[230:231], v[152:153], v[238:239]
	v_pk_fma_f32 v[232:233], v[232:233], v[154:155], v[240:241]
	v_pk_fma_f32 v[234:235], v[234:235], v[156:157], v[242:243]
	v_pk_fma_f32 v[236:237], v[236:237], v[158:159], v[244:245]
	v_cvt_pk_bf16_f32 v160, v230, v231
	v_cvt_pk_bf16_f32 v161, v232, v233
	v_cvt_pk_bf16_f32 v162, v234, v235
	v_cvt_pk_bf16_f32 v163, v236, v237
	global_store_dwordx4 v[74:75], v[160:163], off offset:1536
	v_pk_fma_f32 v[168:169], v[168:169], v[62:63], v[176:177]
	v_pk_fma_f32 v[170:171], v[170:171], v[56:57], v[178:179]
	v_pk_fma_f32 v[172:173], v[172:173], v[58:59], v[180:181]
	v_pk_fma_f32 v[174:175], v[174:175], v[54:55], v[182:183]
	global_store_dwordx4 v[44:45], v[168:171], off offset:512
	global_store_dwordx4 v[44:45], v[172:175], off offset:528
	v_pk_add_f32 v[196:197], v[196:197], 1.0 op_sel_hi:[1,0]
	v_pk_add_f32 v[198:199], v[198:199], 1.0 op_sel_hi:[1,0]
	v_pk_add_f32 v[200:201], v[200:201], 1.0 op_sel_hi:[1,0]
	v_pk_add_f32 v[202:203], v[202:203], 1.0 op_sel_hi:[1,0]
	v_pk_fma_f32 v[196:197], v[196:197], v[168:169], v[204:205]
	v_pk_fma_f32 v[198:199], v[198:199], v[170:171], v[206:207]
	v_pk_fma_f32 v[200:201], v[200:201], v[172:173], v[208:209]
	v_pk_fma_f32 v[202:203], v[202:203], v[174:175], v[210:211]
	v_cvt_pk_bf16_f32 v176, v196, v197
	v_cvt_pk_bf16_f32 v177, v198, v199
	v_cvt_pk_bf16_f32 v178, v200, v201
	v_cvt_pk_bf16_f32 v179, v202, v203
	global_store_dwordx4 v[74:75], v[176:179], off offset:2560
	v_pk_fma_f32 v[214:215], v[214:215], v[14:15], v[222:223]
	v_pk_fma_f32 v[216:217], v[216:217], v[10:11], v[224:225]
	v_pk_fma_f32 v[218:219], v[218:219], v[12:13], v[226:227]
	v_pk_fma_f32 v[220:221], v[220:221], v[8:9], v[228:229]
	global_store_dwordx4 v[44:45], v[214:217], off offset:2560
	global_store_dwordx4 v[44:45], v[218:221], off offset:2576
	s_waitcnt vmcnt(8)
	v_pk_add_f32 v[114:115], v[114:115], 1.0 op_sel_hi:[1,0]
	v_pk_add_f32 v[116:117], v[116:117], 1.0 op_sel_hi:[1,0]
	v_pk_add_f32 v[118:119], v[118:119], 1.0 op_sel_hi:[1,0]
	v_pk_add_f32 v[120:121], v[120:121], 1.0 op_sel_hi:[1,0]
	v_pk_fma_f32 v[114:115], v[114:115], v[214:215], v[122:123]
	v_pk_fma_f32 v[116:117], v[116:117], v[216:217], v[124:125]
	v_pk_fma_f32 v[118:119], v[118:119], v[218:219], v[126:127]
	v_pk_fma_f32 v[120:121], v[120:121], v[220:221], v[128:129]
	v_cvt_pk_bf16_f32 v222, v114, v115
	v_cvt_pk_bf16_f32 v223, v116, v117
	v_cvt_pk_bf16_f32 v224, v118, v119
	v_cvt_pk_bf16_f32 v225, v120, v121
	global_store_dwordx4 v[74:75], v[222:225], off offset:3584
	s_andn2_b64 exec, exec, s[14:15]
	s_cbranch_execnz .LBB0_589
